# cmask rewrite + SSD GG masked-exp blocks made branch-free (LDS reads hoisted)
# baseline (speedup 1.0000x reference)
; __device__ __forceinline__ unsigned f2bf(float f) { return pk2(f, f) & 0xffffu; }
; #define BAR_LDS() asm volatile("s_waitcnt lgkmcnt(0)\n\ts_barrier" ::: "memory")
; template <bool DRY> __device__ __forceinline__ void ssd_unit(const Args& A, char* lds, int b, int h) {
;     ...
;         if (c + 1 < SEQL / 64) { const size_t o = (size_t)(c + 1) * 64 * 2048;
;             pre[0] = *(const bf16x8*)(pB + o); pre[1] = *(const bf16x8*)(pB + o + 32 * 2048); pre[2] = *(const bf16x8*)(pC + o); pre[3] = *(const bf16x8*)(pC + o + 32 * 2048); pre[4] = *(const bf16x8*)(pX + o); }
;         unsigned short zv[2][4];
; #pragma unroll
;         for (int pi = 0; pi < 2; ++pi)
; #pragma unroll
;             for (int r = 0; r < 4; ++r) zv[pi][r] = zn[pi][r];
;         if (c + 1 < SEQL / 64) {
; #pragma unroll
;             for (int pi = 0; pi < 2; ++pi)
; #pragma unroll
;                 for (int r = 0; r < 4; ++r) zn[pi][r] = pZ[((size_t)(c + 1) * 64 + r) * LD0 + 16 * pi]; }
;         BAR_LDS();
;         f32x4m cb[2], ya[2]; cb[0] = (f32x4m){0.f, 0.f, 0.f, 0.f}; cb[1] = cb[0]; ya[0] = cb[0]; ya[1] = cb[0];
; #pragma unroll
;         for (int ks = 0; ks < 4; ++ks) { const bf16x8 af = *(const bf16x8*)(CS + (lt * 16 + fr) * 136 + ks * 32 + 8 * fq);
; #pragma unroll
;             for (int si = 0; si < 2; ++si) { const bf16x8 bfv = *(const bf16x8*)(BS + ((st0 + si) * 16 + fr) * 136 + ks * 32 + 8 * fq); cb[si] = __builtin_amdgcn_mfma_f32_16x16x32_bf16(af, bfv, cb[si], 0, 0, 0); }
; #pragma unroll
;             for (int pi = 0; pi < 2; ++pi) { const bf16x8 sf = *(const bf16x8*)(SBF + ((pt0 + pi) * 16 + fr) * 136 + ks * 32 + 8 * fq); ya[pi] = __builtin_amdgcn_mfma_f32_16x16x32_bf16(af, sf, ya[pi], 0, 0, 0); } }
; #pragma unroll
;         for (int r = 0; r < 4; ++r) { const int l = lt * 16 + 4 * fq + r; const float al = DTA[64 + l];
; #pragma unroll
;             for (int si = 0; si < 2; ++si) { const int s = (st0 + si) * 16 + fr; const float v = (s <= l) ? cb[si][r] * __expf(al - DTA[64 + s]) : 0.f; GG[l * 72 + s] = (bf16)f2bf(v); }
;             const float ea = DTA[128 + l]; ya[0][r] *= ea; ya[1][r] *= ea; }
;         const float decay = __expf(DTA[64 + 63]);
.LBB0_821:
	s_or_b64 exec, exec, s[66:67]
	v_lshl_add_u64 v[16:17], v[76:77], 0, s[56:57]
	v_add_co_u32_e32 v18, vcc, 0x80000, v16
	v_add_u32_e32 v137, v68, v133
	s_nop 0
	v_addc_co_u32_e32 v19, vcc, 0, v17, vcc
	v_add_co_u32_e32 v16, vcc, 0xa0000, v16
	v_add_u32_e32 v138, v68, v134
	s_nop 0
	v_addc_co_u32_e32 v17, vcc, 0, v17, vcc
	v_add_co_u32_e32 v36, vcc, 0x1ca0000, v44
	flat_load_dwordx4 v[20:23], v[18:19] offset:2048
	flat_load_dwordx4 v[28:31], v[18:19] offset:2560
	flat_load_dwordx4 v[24:27], v[16:17] offset:2048
	flat_load_dwordx4 v[32:35], v[16:17] offset:2560
	v_addc_co_u32_e32 v37, vcc, 0, v45, vcc
	v_add_co_u32_e32 v38, vcc, 0x1ca3000, v44
	v_lshl_add_u64 v[16:17], v[80:81], 0, s[58:59]
	s_nop 0
	v_addc_co_u32_e32 v39, vcc, 0, v45, vcc
	v_add_co_u32_e32 v40, vcc, 0x1ca6000, v44
	flat_load_dwordx4 v[16:19], v[16:17]
	s_nop 0
	v_addc_co_u32_e32 v41, vcc, 0, v45, vcc
	v_add_co_u32_e32 v42, vcc, 0x1ca9000, v44
	v_lshl_add_u32 v85, v56, 2, s4
	s_nop 0
	v_addc_co_u32_e32 v43, vcc, 0, v45, vcc
	flat_load_ushort v131, v[36:37]
	flat_load_ushort v145, v[38:39] offset:1024
	flat_load_ushort v146, v[40:41] offset:2048
	flat_load_ushort v129, v[42:43] offset:3072
	flat_load_ushort v67, v[42:43] offset:3104
	flat_load_ushort v147, v[40:41] offset:2080
	flat_load_ushort v148, v[38:39] offset:1056
	flat_load_ushort v130, v[36:37] offset:32
	s_waitcnt lgkmcnt(0)
	s_barrier
	ds_read_b128 v[36:39], v64
	ds_read_b128 v[40:43], v137 offset:17408
	v_add_u32_e32 v142, v125, v133
	v_add_u32_e32 v139, v125, v134
	ds_read_b128 v[44:47], v138 offset:17408
	ds_read_b128 v[88:91], v64 offset:192
	ds_read_b32 v82, v85 offset:256
	ds_read_b128 v[48:51], v142
	ds_read_b128 v[150:153], v137 offset:17600
	ds_read_b128 v[154:157], v139
	ds_read_b128 v[158:161], v138 offset:17600
	s_waitcnt lgkmcnt(0)
	v_mfma_f32_16x16x32_bf16 v[40:43], v[36:39], v[40:43], 0
	ds_read_b128 v[162:165], v64 offset:64
	ds_read_b128 v[166:169], v142 offset:192
	v_lshl_add_u32 v87, v65, 2, s4
	v_mov_b32_e32 v83, 0
	v_mfma_f32_16x16x32_bf16 v[44:47], v[36:39], v[44:47], 0
	v_mfma_f32_16x16x32_bf16 v[48:51], v[36:39], v[48:51], 0
	v_mfma_f32_16x16x32_bf16 v[36:39], v[36:39], v[154:157], 0
	ds_read_b128 v[154:157], v137 offset:17472
	ds_read_b128 v[170:173], v64 offset:128
	ds_read_b128 v[174:177], v137 offset:17536
	s_waitcnt lgkmcnt(0)
	v_mfma_f32_16x16x32_bf16 v[40:43], v[162:165], v[154:157], v[40:43]
	ds_read_b128 v[154:157], v138 offset:17472
	ds_read_b128 v[178:181], v138 offset:17536
	s_waitcnt lgkmcnt(0)
	v_mfma_f32_16x16x32_bf16 v[44:47], v[162:165], v[154:157], v[44:47]
	ds_read_b128 v[154:157], v142 offset:64
	ds_read_b128 v[182:185], v142 offset:128
	s_waitcnt lgkmcnt(0)
	v_mfma_f32_16x16x32_bf16 v[48:51], v[162:165], v[154:157], v[48:51]
	ds_read_b128 v[154:157], v139 offset:64
	ds_read_b128 v[186:189], v139 offset:128
	v_mfma_f32_16x16x32_bf16 v[40:43], v[170:173], v[174:177], v[40:43]
	s_waitcnt lgkmcnt(0)
	v_mfma_f32_16x16x32_bf16 v[36:39], v[162:165], v[154:157], v[36:39]
	v_mfma_f32_16x16x32_bf16 v[154:157], v[170:173], v[182:185], v[48:51]
	v_mfma_f32_16x16x32_bf16 v[48:51], v[88:91], v[150:153], v[40:43]
	ds_read_b128 v[150:153], v139 offset:192
	v_mfma_f32_16x16x32_bf16 v[44:47], v[170:173], v[178:181], v[44:47]
	v_mfma_f32_16x16x32_bf16 v[36:39], v[170:173], v[186:189], v[36:39]
	v_mfma_f32_16x16x32_bf16 v[44:47], v[88:91], v[158:161], v[44:47]
	v_mfma_f32_16x16x32_bf16 v[40:43], v[88:91], v[166:169], v[154:157]
	s_waitcnt lgkmcnt(0)
	v_mfma_f32_16x16x32_bf16 v[36:39], v[88:91], v[150:153], v[36:39]
	v_lshl_add_u32 v88, v99, 2, s4
	v_mov_b32_e32 v89, s4
	ds_read_b32 v190, v87 offset:256
	ds_read_b32 v191, v88 offset:256
	ds_read2_b32 v[192:193], v85 offset0:65 offset1:66
	ds_read2_b32 v[194:195], v85 offset0:67 offset1:128
	ds_read2_b32 v[196:197], v85 offset0:129 offset1:130
	ds_read_b32 v198, v85 offset:524
	ds_read_b32 v199, v89 offset:508
	s_waitcnt lgkmcnt(0)
	v_sub_f32_e32 v200, v82, v190
	v_sub_f32_e32 v201, v82, v191
	v_sub_f32_e32 v202, v192, v190
	v_sub_f32_e32 v203, v192, v191
	v_sub_f32_e32 v204, v193, v190
	v_sub_f32_e32 v205, v193, v191
	v_sub_f32_e32 v206, v194, v190
	v_sub_f32_e32 v207, v194, v191
	v_mul_f32_e32 v200, 0x3fb8aa3b, v200
	v_mul_f32_e32 v201, 0x3fb8aa3b, v201
	v_mul_f32_e32 v202, 0x3fb8aa3b, v202
	v_mul_f32_e32 v203, 0x3fb8aa3b, v203
	v_mul_f32_e32 v204, 0x3fb8aa3b, v204
	v_mul_f32_e32 v205, 0x3fb8aa3b, v205
	v_mul_f32_e32 v206, 0x3fb8aa3b, v206
	v_mul_f32_e32 v207, 0x3fb8aa3b, v207
	v_exp_f32_e32 v200, v200
	v_exp_f32_e32 v201, v201
	v_exp_f32_e32 v202, v202
	v_exp_f32_e32 v203, v203
	v_exp_f32_e32 v204, v204
	v_exp_f32_e32 v205, v205
	v_exp_f32_e32 v206, v206
	v_exp_f32_e32 v207, v207
	v_mul_f32_e32 v200, v48, v200
	v_mul_f32_e32 v201, v44, v201
	v_mul_f32_e32 v202, v49, v202
	v_mul_f32_e32 v203, v45, v203
	v_mul_f32_e32 v204, v50, v204
	v_mul_f32_e32 v205, v46, v205
	v_mul_f32_e32 v206, v51, v206
	v_mul_f32_e32 v207, v47, v207
	v_cndmask_b32_e64 v200, 0, v200, s[6:7]
	v_cndmask_b32_e64 v201, 0, v201, s[8:9]
	v_cndmask_b32_e64 v202, 0, v202, s[10:11]
	v_cndmask_b32_e64 v203, 0, v203, s[12:13]
	v_cndmask_b32_e64 v204, 0, v204, s[14:15]
	v_cndmask_b32_e64 v205, 0, v205, s[16:17]
	v_cndmask_b32_e64 v206, 0, v206, s[18:19]
	v_cndmask_b32_e64 v207, 0, v207, s[20:21]
	v_cvt_pk_bf16_f32 v200, v200, s0
	v_cvt_pk_bf16_f32 v201, v201, s0
	v_cvt_pk_bf16_f32 v202, v202, s0
	v_cvt_pk_bf16_f32 v203, v203, s0
	v_cvt_pk_bf16_f32 v204, v204, s0
	v_cvt_pk_bf16_f32 v205, v205, s0
	v_cvt_pk_bf16_f32 v206, v206, s0
	v_cvt_pk_bf16_f32 v207, v207, s0
	ds_write_b16 v108, v200
	ds_write_b16 v107, v201
	ds_write_b16 v112, v202
	ds_write_b16 v111, v203
	ds_write_b16 v115, v204
	ds_write_b16 v114, v205
	ds_write_b16 v116, v206
	ds_write_b16 v119, v207
	v_mov_b32_e32 v83, v195
	v_mov_b32_e32 v45, v196
	v_mov_b32_e32 v49, v197
	v_mov_b32_e32 v50, v198
	v_mov_b32_e32 v51, v199
	s_waitcnt lgkmcnt(0)
	s_barrier
; __device__ __forceinline__ unsigned f2bf(float f) { return pk2(f, f) & 0xffffu; }
; __device__ __forceinline__ float bf2f(unsigned short h) { return __uint_as_float(((unsigned)h) << 16); }
; template <bool DRY> __device__ __forceinline__ void ssd_unit(const Args& A, char* lds, int b, int h) {
;     ...
;             const float ea = DTA[128 + l]; ya[0][r] *= ea; ya[1][r] *= ea; }
;         const float decay = __expf(DTA[64 + 63]);
;         BAR_LDS();
; #pragma unroll
;         for (int ks = 0; ks < 2; ++ks) { const bf16x8 gf = *(const bf16x8*)(GG + (lt * 16 + fr) * 72 + ks * 32 + 8 * fq);
; #pragma unroll
;             for (int pi = 0; pi < 2; ++pi) { const int p = (pt0 + pi) * 16 + fr; const bf16x8 xf = *(const bf16x8*)(XT + p * 72 + (((ks * 4 + fq) ^ ((p >> 3) & 7)) << 3)); ya[pi] = __builtin_amdgcn_mfma_f32_16x16x32_bf16(gf, xf, ya[pi], 0, 0, 0); } }
; #pragma unroll
;         for (int pi = 0; pi < 2; ++pi)
; #pragma unroll
;             for (int ni = 0; ni < 2; ++ni) sta[pi][ni] = sta[pi][ni] * decay;
; #pragma unroll
;         for (int ks = 0; ks < 2; ++ks) { bf16x8 bt[2];
; #pragma unroll
;             for (int ni = 0; ni < 2; ++ni) { const int n = (nt0 + ni) * 16 + fr; bt[ni] = *(const bf16x8*)(BST + n * 72 + (((ks * 4 + fq) ^ ((n >> 3) & 7)) << 3)); }
; #pragma unroll
;             for (int pi = 0; pi < 2; ++pi) { const int p = (pt0 + pi) * 16 + fr; const bf16x8 xw = *(const bf16x8*)(XWT + p * 72 + (((ks * 4 + fq) ^ ((p >> 3) & 7)) << 3));
; #pragma unroll
;                 for (int ni = 0; ni < 2; ++ni) sta[pi][ni] = __builtin_amdgcn_mfma_f32_16x16x32_bf16(xw, bt[ni], sta[pi][ni], 0, 0, 0); } }
; #pragma unroll
;         for (int pi = 0; pi < 2; ++pi)
; #pragma unroll
;             for (int ni = 0; ni < 2; ++ni)
; #pragma unroll
;                 for (int r = 0; r < 4; ++r) SBF[((pt0 + pi) * 16 + 4 * fq + r) * 136 + (nt0 + ni) * 16 + fr] = (bf16)f2bf(sta[pi][ni][r]);
; #pragma unroll
;         for (int pi = 0; pi < 2; ++pi)
; #pragma unroll
;             for (int r = 0; r < 4; ++r) { const int l = lt * 16 + 4 * fq + r, p = (pt0 + pi) * 16 + fr;
;                 const float y = ya[pi][r] + Dh * bf2f(XS[l * 72 + p]);
;                 const float z = bf2f(zv[pi][r]); const float gt = y * silu_f(z);
;                 gts[pi][r] = (unsigned short)f2bf(gt); sqs[pi][r] = row_sum16(gt * gt); }
	s_waitcnt lgkmcnt(0)
	v_mul_f32_e32 v42, v42, v49
	v_mul_f32_e32 v38, v38, v49
	ds_read_b128 v[46:49], v113
	ds_read_b128 v[88:91], v106 offset:53248
	ds_read_b128 v[150:153], v104 offset:53248
	ds_read_b128 v[154:157], v113 offset:64
	ds_read_b128 v[158:161], v106 offset:62464
	v_mul_f32_e32 v41, v41, v45
	v_mul_f32_e32 v37, v37, v45
	v_mul_f32_e32 v40, v40, v83
	v_mul_f32_e32 v36, v36, v83
	v_mul_f32_e32 v43, v43, v50
	v_mul_f32_e32 v39, v39, v50
	v_mul_f32_e32 v82, 0x3fb8aa3b, v51
	s_waitcnt lgkmcnt(0)
	v_mfma_f32_16x16x32_bf16 v[40:43], v[46:49], v[88:91], v[40:43]
	ds_read_b128 v[88:91], v102 offset:53248
	ds_read_b128 v[162:165], v104 offset:62464
	v_exp_f32_e32 v82, v82
	v_add_u32_e32 v141, v127, v135
	v_mfma_f32_16x16x32_bf16 v[44:47], v[46:49], v[150:153], v[36:39]
	ds_read_b128 v[48:51], v101 offset:53248
	ds_read_b128 v[150:153], v102 offset:62464
	v_pk_mul_f32 v[14:15], v[14:15], v[82:83] op_sel_hi:[1,0]
	v_pk_mul_f32 v[12:13], v[12:13], v[82:83] op_sel_hi:[1,0]
	s_waitcnt lgkmcnt(0)
	v_mfma_f32_16x16x32_bf16 v[36:39], v[154:157], v[88:91], v[40:43]
	ds_read_b128 v[88:91], v103 offset:34816
	ds_read_b128 v[166:169], v101 offset:62464
	v_pk_mul_f32 v[10:11], v[10:11], v[82:83] op_sel_hi:[1,0]
	v_pk_mul_f32 v[8:9], v[8:9], v[82:83] op_sel_hi:[1,0]
	v_mfma_f32_16x16x32_bf16 v[40:43], v[154:157], v[48:51], v[44:47]
	v_mul_f32_e64 v6, v6, v82
	v_mul_f32_e64 v7, v7, v82
	v_pk_mul_f32 v[4:5], v[4:5], v[82:83] op_sel_hi:[1,0]
	v_pk_mul_f32 v[2:3], v[2:3], v[82:83] op_sel_hi:[1,0]
	ds_read_b128 v[44:47], v118 offset:34816
	s_waitcnt lgkmcnt(0)
	v_mfma_f32_16x16x32_bf16 v[12:15], v[158:161], v[88:91], v[12:15]
	v_mul_f32_e64 v0, v0, v82
	v_mul_f32_e64 v1, v1, v82
	v_add_u32_e32 v143, v128, v135
	v_add_u32_e32 v144, v127, v136
	v_mfma_f32_16x16x32_bf16 v[8:11], v[158:161], v[44:47], v[8:11]
	v_add_u32_e32 v140, v128, v136
	s_add_i32 s1, s1, 1
	s_and_b64 vcc, exec, s[26:27]
	v_mfma_f32_16x16x32_bf16 v[4:7], v[162:165], v[44:47], v[4:7]
	ds_read_b128 v[44:47], v121 offset:34816
	ds_read_b128 v[48:51], v122 offset:34816
	v_mfma_f32_16x16x32_bf16 v[0:3], v[162:165], v[88:91], v[0:3]
	v_lshlrev_b32_e32 v88, 16, v86
	v_and_b32_e32 v89, 0xffff0000, v86
	s_waitcnt lgkmcnt(0)
	v_mfma_f32_16x16x32_bf16 v[12:15], v[150:153], v[44:47], v[12:15]
	v_mfma_f32_16x16x32_bf16 v[8:11], v[150:153], v[48:51], v[8:11]
	v_mfma_f32_16x16x32_bf16 v[0:3], v[166:169], v[44:47], v[0:3]
	s_nop 5
	v_cvt_pk_bf16_f32 v44, v12, s0
	ds_write_b16 v141, v44
	v_cvt_pk_bf16_f32 v44, v13, s0
	ds_write_b16 v141, v44 offset:272
	v_cvt_pk_bf16_f32 v44, v14, s0
	ds_write_b16 v141, v44 offset:544
	v_cvt_pk_bf16_f32 v44, v15, s0
	ds_write_b16 v141, v44 offset:816
	v_cvt_pk_bf16_f32 v44, v8, s0
	ds_write_b16 v143, v44
	v_cvt_pk_bf16_f32 v44, v9, s0
	ds_write_b16 v143, v44 offset:272
	v_cvt_pk_bf16_f32 v44, v10, s0
	ds_write_b16 v143, v44 offset:544
	v_cvt_pk_bf16_f32 v44, v11, s0
	v_mfma_f32_16x16x32_bf16 v[4:7], v[166:169], v[48:51], v[4:7]
	ds_write_b16 v143, v44 offset:816
	v_cvt_pk_bf16_f32 v44, v0, s0
	ds_write_b16 v144, v44
	v_cvt_pk_bf16_f32 v44, v1, s0
	ds_write_b16 v144, v44 offset:272
	v_cvt_pk_bf16_f32 v44, v2, s0
	ds_write_b16 v144, v44 offset:544
	v_cvt_pk_bf16_f32 v44, v3, s0
	ds_write_b16 v144, v44 offset:816
	v_cvt_pk_bf16_f32 v44, v4, s0
	ds_write_b16 v140, v44
	v_cvt_pk_bf16_f32 v44, v5, s0
	ds_write_b16 v140, v44 offset:272
	v_cvt_pk_bf16_f32 v44, v6, s0
	ds_write_b16 v140, v44 offset:544
	v_cvt_pk_bf16_f32 v44, v7, s0
	v_lshlrev_b32_e32 v45, 16, v97
	ds_write_b16 v140, v44 offset:816
	v_mul_f32_e32 v44, 0xbfb8aa3b, v45
	v_exp_f32_e32 v44, v44
	ds_read_u16 v46, v110
	ds_read_u16 v47, v110 offset:144
	ds_read_u16 v48, v110 offset:288
	ds_read_u16 v97, v110 offset:432
	ds_read_u16 v82, v105
	ds_read_u16 v87, v105 offset:144
	ds_read_u16 v90, v105 offset:288
	ds_read_u16 v93, v105 offset:432
	s_waitcnt lgkmcnt(0)
; __device__ __forceinline__ unsigned f2bf(float f) { return pk2(f, f) & 0xffffu; }
; __device__ __forceinline__ float bf2f(unsigned short h) { return __uint_as_float(((unsigned)h) << 16); }
; template <int CTRL> __device__ __forceinline__ float dppf(float old, float src) { return __builtin_bit_cast(float, __builtin_amdgcn_update_dpp(__builtin_bit_cast(int, old), __builtin_bit_cast(int, src), CTRL, 0xF, 0xF, false)); }
; __device__ __forceinline__ float silu_f(float x) { return x * __builtin_amdgcn_rcpf(1.f + __expf(-x)); }
; __device__ __forceinline__ float row_sum16(float v) { v += dppf<0xB1>(v, v); v += dppf<0x4E>(v, v); v += dppf<0x141>(v, v); v += dppf<0x140>(v, v); return v; }
; __device__ __forceinline__ float rdlane(float v, int l) { return __builtin_bit_cast(float, __builtin_amdgcn_readlane(__builtin_bit_cast(int, v), l)); }
; __device__ __forceinline__ float wave_sum(float v) { v = row_sum16(v); return (rdlane(v, 0) + rdlane(v, 16)) + (rdlane(v, 32) + rdlane(v, 48)); }
; __device__ __forceinline__ float wave_scan(float x, int lane) {
;     x += dppf<0x111>(0.f, x); x += dppf<0x112>(0.f, x); x += dppf<0x114>(0.f, x); x += dppf<0x118>(0.f, x);
;     const float t0 = rdlane(x, 15), t1 = rdlane(x, 31), t2 = rdlane(x, 47); const int rw = lane >> 4;
;     return x + (rw == 0 ? 0.f : (rw == 1 ? t0 : (rw == 2 ? t0 + t1 : (t0 + t1) + t2)));
; template <bool DRY> __device__ __forceinline__ void ssd_unit(const Args& A, char* lds, int b, int h) {
;     ...
;             for (int r = 0; r < 4; ++r) { const int l = lt * 16 + 4 * fq + r, p = (pt0 + pi) * 16 + fr;
;                 const float y = ya[pi][r] + Dh * bf2f(XS[l * 72 + p]);
;                 const float z = bf2f(zv[pi][r]); const float gt = y * silu_f(z);
;                 gts[pi][r] = (unsigned short)f2bf(gt); sqs[pi][r] = row_sum16(gt * gt); }
;         if (wave == 0 && c + 1 < SEQL / 64) { float* DN = DTA0 + ((c + 1) & 1) * 256; const float s = wave_scan(Ah * dtn, lane); const float tot = rdlane(s, 63);
;             DN[lane] = dtn; DN[64 + lane] = s; DN[128 + lane] = __expf(s); DN[192 + lane] = __expf(tot - s);
;             if (c + 2 < SEQL / 64) dtn = DT[(m0 + 128 + lane) * 16 + h]; }
	v_lshlrev_b32_e32 v46, 16, v46
	v_fma_f32 v36, v54, v46, v36
	v_add_f32_e32 v44, 1.0, v44
	v_rcp_f32_e32 v46, v44
	v_lshlrev_b32_e32 v44, 16, v84
	v_mul_f32_e32 v49, 0xbfb8aa3b, v44
	v_exp_f32_e32 v49, v49
	v_mul_f32_e32 v45, v46, v45
	v_mul_f32_e32 v36, v45, v36
	v_and_b32_e32 v45, 0xffff0000, v84
	v_add_f32_e32 v46, 1.0, v49
	v_mul_f32_e32 v49, 0xbfb8aa3b, v45
	v_exp_f32_e32 v50, v49
	v_lshlrev_b32_e32 v49, 16, v48
	v_lshlrev_b32_e32 v48, 16, v47
	v_rcp_f32_e32 v46, v46
	v_add_f32_e32 v47, 1.0, v50
	v_rcp_f32_e32 v47, v47
	v_mov_b32_e32 v50, v37
	v_mov_b32_e32 v51, v38
	v_pk_fma_f32 v[48:49], v[54:55], v[48:49], v[50:51]
	v_pk_mul_f32 v[44:45], v[46:47], v[44:45]
	v_lshlrev_b32_e32 v91, 16, v90
	v_pk_mul_f32 v[44:45], v[44:45], v[48:49]
	v_lshlrev_b32_e32 v90, 16, v87
	v_pk_mov_b32 v[46:47], v[44:45], v[44:45] op_sel:[1,0]
	s_nop 0
	v_mov_b32_e32 v37, v47
	v_pk_mul_f32 v[48:49], v[36:37], v[36:37]
	v_lshlrev_b32_e32 v47, 16, v82
	v_fma_f32 v40, v54, v47, v40
	v_mov_b32_dpp v48, v48 quad_perm:[1,0,3,2] row_mask:0xf bank_mask:0xf
	v_mov_b32_dpp v49, v49 quad_perm:[1,0,3,2] row_mask:0xf bank_mask:0xf
	v_pk_fma_f32 v[48:49], v[36:37], v[36:37], v[48:49]
	v_lshlrev_b32_e32 v37, 16, v96
	v_mul_f32_e32 v38, 0xbfb8aa3b, v37
	v_exp_f32_e32 v38, v38
	v_mov_b32_e32 v50, v48
	v_mov_b32_e32 v51, v49
	v_add_f32_e32 v38, 1.0, v38
	v_rcp_f32_e32 v38, v38
	v_mov_b32_dpp v50, v50 quad_perm:[2,3,0,1] row_mask:0xf bank_mask:0xf
	v_mov_b32_dpp v51, v51 quad_perm:[2,3,0,1] row_mask:0xf bank_mask:0xf
	v_pk_add_f32 v[48:49], v[48:49], v[50:51]
	v_mul_f32_e32 v37, v38, v37
	v_mul_f32_e32 v47, v37, v40
	v_mul_f32_e32 v37, 0xbfb8aa3b, v88
	v_exp_f32_e32 v37, v37
	v_mul_f32_e32 v38, 0xbfb8aa3b, v89
	v_exp_f32_e32 v38, v38
	v_mov_b32_e32 v40, v41
	v_add_f32_e32 v37, 1.0, v37
	v_rcp_f32_e32 v86, v37
	v_add_f32_e32 v37, 1.0, v38
	v_rcp_f32_e32 v87, v37
	v_mov_b32_e32 v41, v42
	v_pk_fma_f32 v[40:41], v[54:55], v[90:91], v[40:41]
	v_mov_b32_e32 v42, v39
	v_pk_mul_f32 v[86:87], v[86:87], v[88:89]
	v_pk_mul_f32 v[82:83], v[46:47], v[46:47]
	v_pk_mul_f32 v[86:87], v[86:87], v[40:41]
	v_mov_b32_e32 v50, v48
	v_pk_mul_f32 v[40:41], v[86:87], v[86:87]
	v_mov_b32_dpp v82, v82 quad_perm:[1,0,3,2] row_mask:0xf bank_mask:0xf
	v_mov_b32_dpp v83, v83 quad_perm:[1,0,3,2] row_mask:0xf bank_mask:0xf
	v_mov_b32_dpp v40, v40 quad_perm:[1,0,3,2] row_mask:0xf bank_mask:0xf
	v_mov_b32_dpp v41, v41 quad_perm:[1,0,3,2] row_mask:0xf bank_mask:0xf
	v_pk_fma_f32 v[40:41], v[86:87], v[86:87], v[40:41]
	v_pk_fma_f32 v[82:83], v[46:47], v[46:47], v[82:83]
	v_mov_b32_e32 v88, v40
	v_mov_b32_e32 v89, v41
	v_mov_b32_e32 v84, v82
	v_mov_b32_dpp v88, v88 quad_perm:[2,3,0,1] row_mask:0xf bank_mask:0xf
	v_mov_b32_dpp v89, v89 quad_perm:[2,3,0,1] row_mask:0xf bank_mask:0xf
	v_pk_add_f32 v[40:41], v[40:41], v[88:89]
	v_mov_b32_e32 v85, v83
	v_mov_b32_e32 v88, v40
	v_mov_b32_e32 v89, v41
	v_mov_b32_dpp v84, v84 quad_perm:[2,3,0,1] row_mask:0xf bank_mask:0xf
	v_mov_b32_dpp v88, v88 row_half_mirror row_mask:0xf bank_mask:0xf
	v_mov_b32_dpp v89, v89 row_half_mirror row_mask:0xf bank_mask:0xf
	v_pk_add_f32 v[88:89], v[40:41], v[88:89]
	v_lshlrev_b32_e32 v40, 16, v94
	v_mul_f32_e32 v37, 0xbfb8aa3b, v40
	v_lshlrev_b32_e32 v41, 16, v95
	v_exp_f32_e32 v37, v37
	v_mul_f32_e32 v38, 0xbfb8aa3b, v41
	v_exp_f32_e32 v38, v38
	v_lshlrev_b32_e32 v95, 16, v93
	v_add_f32_e32 v37, 1.0, v37
	v_rcp_f32_e32 v92, v37
	v_add_f32_e32 v37, 1.0, v38
	v_rcp_f32_e32 v93, v37
	v_lshlrev_b32_e32 v94, 16, v97
	v_pk_fma_f32 v[38:39], v[54:55], v[94:95], v[42:43]
	v_mov_b32_dpp v85, v85 quad_perm:[2,3,0,1] row_mask:0xf bank_mask:0xf
	v_pk_mul_f32 v[40:41], v[92:93], v[40:41]
	v_pk_add_f32 v[82:83], v[82:83], v[84:85]
	v_pk_mul_f32 v[92:93], v[40:41], v[38:39]
	v_mov_b32_e32 v51, v49
	v_pk_mul_f32 v[38:39], v[92:93], v[92:93]
	v_mov_b32_e32 v84, v82
	v_mov_b32_e32 v85, v83
	v_mov_b32_dpp v38, v38 quad_perm:[1,0,3,2] row_mask:0xf bank_mask:0xf
	v_mov_b32_dpp v39, v39 quad_perm:[1,0,3,2] row_mask:0xf bank_mask:0xf
	v_pk_fma_f32 v[38:39], v[92:93], v[92:93], v[38:39]
	v_mov_b32_dpp v50, v50 row_half_mirror row_mask:0xf bank_mask:0xf
	v_mov_b32_e32 v40, v38
	v_mov_b32_e32 v41, v39
	v_mov_b32_dpp v51, v51 row_half_mirror row_mask:0xf bank_mask:0xf
	v_mov_b32_dpp v40, v40 quad_perm:[2,3,0,1] row_mask:0xf bank_mask:0xf
	v_mov_b32_dpp v41, v41 quad_perm:[2,3,0,1] row_mask:0xf bank_mask:0xf
	v_pk_add_f32 v[38:39], v[38:39], v[40:41]
	v_mov_b32_dpp v84, v84 row_half_mirror row_mask:0xf bank_mask:0xf
	v_mov_b32_e32 v40, v38
	v_mov_b32_e32 v41, v39
	v_mov_b32_dpp v85, v85 row_half_mirror row_mask:0xf bank_mask:0xf
	v_mov_b32_dpp v40, v40 row_half_mirror row_mask:0xf bank_mask:0xf
	v_mov_b32_dpp v41, v41 row_half_mirror row_mask:0xf bank_mask:0xf
	v_pk_add_f32 v[48:49], v[48:49], v[50:51]
	v_pk_add_f32 v[82:83], v[82:83], v[84:85]
	v_pk_add_f32 v[94:95], v[38:39], v[40:41]
	v_mov_b32_e32 v50, v48
	v_mov_b32_e32 v51, v49
	v_mov_b32_e32 v84, v82
	v_mov_b32_e32 v85, v83
	v_mov_b32_e32 v90, v88
	v_mov_b32_e32 v91, v89
	v_mov_b32_e32 v96, v94
	v_mov_b32_e32 v97, v95
	v_mov_b32_dpp v50, v50 row_mirror row_mask:0xf bank_mask:0xf
	v_mov_b32_dpp v51, v51 row_mirror row_mask:0xf bank_mask:0xf
	v_mov_b32_dpp v84, v84 row_mirror row_mask:0xf bank_mask:0xf
	v_mov_b32_dpp v85, v85 row_mirror row_mask:0xf bank_mask:0xf
	v_mov_b32_dpp v90, v90 row_mirror row_mask:0xf bank_mask:0xf
	v_mov_b32_dpp v91, v91 row_mirror row_mask:0xf bank_mask:0xf
	v_mov_b32_dpp v96, v96 row_mirror row_mask:0xf bank_mask:0xf
	v_mov_b32_dpp v97, v97 row_mirror row_mask:0xf bank_mask:0xf
	s_cbranch_vccnz .LBB0_846
	v_mul_f32_e64 v37, v69, -v100
	v_mov_b32_e32 v38, 0
	s_nop 1
	v_mov_b32_dpp v38, v37 row_shr:1 row_mask:0xf bank_mask:0xf
	v_fma_f32 v37, v69, -v100, v38
	v_mov_b32_e32 v38, 0
	s_nop 0
	v_add_f32_dpp v37, v37, v37 row_shr:2 row_mask:0xf bank_mask:0xf bound_ctrl:1
	s_nop 1
	v_add_f32_dpp v37, v37, v37 row_shr:4 row_mask:0xf bank_mask:0xf bound_ctrl:1
	s_nop 1
	v_add_f32_dpp v37, v37, v37 row_shr:8 row_mask:0xf bank_mask:0xf bound_ctrl:1
	s_nop 0
	v_readlane_b32 s4, v37, 15
	v_readlane_b32 s33, v37, 31
	v_readlane_b32 s5, v37, 47
	s_and_saveexec_b64 s[66:67], s[24:25]
	s_cbranch_execz .LBB0_844
	v_cmp_lt_i32_e32 vcc, 1, v98
	s_mov_b64 s[68:69], 0
	s_and_saveexec_b64 s[42:43], vcc
	s_xor_b64 s[70:71], exec, s[42:43]
	s_cbranch_execnz .LBB0_848
	s_andn2_saveexec_b64 s[70:71], s[70:71]
	s_cbranch_execnz .LBB0_851
